# B2 scan: three input buffers so the scanner prefetches across chunk boundaries (one barrier per 16 steps, no refill bubble)
# speedup vs baseline: 1.0065x; 1.0020x over previous
.Lb2_u_loop:
	s_waitcnt vmcnt(0) lgkmcnt(0)
	s_barrier
	s_and_b32 s20, s22, 7
	s_lshl_b32 s20, s20, 3
	s_lshr_b32 s21, s22, 5
	s_add_i32 s20, s20, s21
	s_bfe_u32 s33, s22, 0x20003
	s_mul_i32 s28, s20, 0x300000
	s_add_u32 s28, s28, 0xcf90000
	s_add_u32 s28, s94, s28
	s_addc_u32 s29, s95, 0
	v_readfirstlane_b32 s21, v133
	s_cmpk_lt_u32 s21, 0x100
	s_cbranch_scc0 .Lb2_loader
	v_lshrrev_b32_e32 v112, 4, v133
	v_and_b32_e32 v113, 15, v133
	v_lshlrev_b32_e32 v8, 4, v113
	s_lshl_b32 s21, s33, 4
	s_addk_i32 s21, 0x140
	v_add_u32_e32 v9, s21, v112
	v_lshlrev_b32_e32 v9, 2, v9
	v_lshlrev_b32_e32 v10, 6, v112
	v_lshl_add_u32 v10, v113, 2, v10
	v_add_u32_e32 v10, 0x12000, v10
	v_lshlrev_b32_e32 v11, 8, v112
	v_lshl_add_u32 v11, v113, 4, v11
	s_lshl_b32 s21, s76, 6
	s_add_i32 s21, s21, s20
	s_lshl_b32 s21, s21, 14
	s_lshl_b32 s23, s33, 12
	s_add_i32 s21, s21, s23
	s_add_u32 s21, s21, 0x412c000
	s_add_u32 s40, s92, s21
	s_addc_u32 s41, s93, 0
	v_mov_b32_e32 v0, 0
	v_mov_b32_e32 v1, 0
	v_mov_b32_e32 v2, 0
	v_mov_b32_e32 v3, 0
	s_movk_i32 s34, 0x80
	s_mov_b32 s0, 0
	s_mov_b32 s1, 0x6000
	s_mov_b32 s24, 0x4000
	v_mov_b32_e32 v114, v8
	v_mov_b32_e32 v115, v9
	v_add_u32_e32 v116, s1, v8
	v_add_u32_e32 v117, s1, v9
	s_setprio 2
	s_barrier
	ds_read_b128 v[12:15], v114 offset:0
	ds_read_b128 v[16:19], v114 offset:256
	ds_read_b128 v[20:23], v114 offset:512
	ds_read_b128 v[24:27], v114 offset:768
	ds_read_b128 v[28:31], v114 offset:1024
	ds_read_b32 v32, v115 offset:0
	ds_read_b128 v[36:39], v114 offset:1536
	ds_read_b128 v[40:43], v114 offset:1792
	ds_read_b128 v[44:47], v114 offset:2048
	ds_read_b128 v[48:51], v114 offset:2304
	ds_read_b128 v[52:55], v114 offset:2560
	ds_read_b32 v56, v115 offset:1536
	ds_read_b128 v[68:71], v114 offset:3072
	ds_read_b128 v[72:75], v114 offset:3328
	ds_read_b128 v[76:79], v114 offset:3584
	ds_read_b128 v[80:83], v114 offset:3840
	ds_read_b128 v[84:87], v114 offset:4096
	ds_read_b32 v88, v115 offset:3072
	s_waitcnt lgkmcnt(0)
.Lb2_scan_loop:
	s_waitcnt lgkmcnt(14)
	v_pk_mul_f32 v[4:5], v[0:1], v[16:17]
	v_pk_mul_f32 v[6:7], v[0:1], v[28:29]
	v_pk_fma_f32 v[4:5], v[2:3], v[18:19], v[4:5]
	v_pk_fma_f32 v[6:7], v[2:3], v[30:31], v[6:7]
	v_add_f32_e32 v4, v4, v5
	v_add_f32_e32 v6, v6, v7
	v_pk_mul_f32 v[0:1], v[0:1], v[12:13]
	v_add_f32_dpp v4, v4, v4 quad_perm:[1,0,3,2] row_mask:0xf bank_mask:0xf bound_ctrl:1
	v_pk_mul_f32 v[2:3], v[2:3], v[14:15]
	ds_write_b32 v10, v6 offset:0
	v_add_f32_dpp v4, v4, v4 quad_perm:[2,3,0,1] row_mask:0xf bank_mask:0xf bound_ctrl:1
	v_pk_fma_f32 v[0:1], v[32:33], v[24:25], v[0:1] op_sel_hi:[0,1,1]
	v_pk_fma_f32 v[2:3], v[32:33], v[26:27], v[2:3] op_sel_hi:[0,1,1]
	v_add_f32_dpp v4, v4, v4 row_half_mirror row_mask:0xf bank_mask:0xf bound_ctrl:1
	ds_read_b128 v[92:95], v114 offset:4608
	ds_read_b128 v[96:99], v114 offset:4864
	v_add_f32_dpp v4, v4, v4 row_mirror row_mask:0xf bank_mask:0xf bound_ctrl:1
	v_pk_fma_f32 v[0:1], v[4:5], v[20:21], v[0:1] op_sel_hi:[0,1,1] neg_lo:[1,0,0] neg_hi:[1,0,0]
	v_pk_fma_f32 v[2:3], v[4:5], v[22:23], v[2:3] op_sel_hi:[0,1,1] neg_lo:[1,0,0] neg_hi:[1,0,0]
	ds_read_b128 v[100:103], v114 offset:5120
	ds_read_b128 v[104:107], v114 offset:5376
	ds_read_b128 v[108:111], v114 offset:5632
	ds_read_b32 v112, v115 offset:4608
	s_waitcnt lgkmcnt(14)
	v_pk_mul_f32 v[4:5], v[0:1], v[40:41]
	v_pk_mul_f32 v[6:7], v[0:1], v[52:53]
	v_pk_fma_f32 v[4:5], v[2:3], v[42:43], v[4:5]
	v_pk_fma_f32 v[6:7], v[2:3], v[54:55], v[6:7]
	v_add_f32_e32 v4, v4, v5
	v_add_f32_e32 v6, v6, v7
	v_pk_mul_f32 v[0:1], v[0:1], v[36:37]
	v_add_f32_dpp v4, v4, v4 quad_perm:[1,0,3,2] row_mask:0xf bank_mask:0xf bound_ctrl:1
	v_pk_mul_f32 v[2:3], v[2:3], v[38:39]
	ds_write_b32 v10, v6 offset:1024
	v_add_f32_dpp v4, v4, v4 quad_perm:[2,3,0,1] row_mask:0xf bank_mask:0xf bound_ctrl:1
	v_pk_fma_f32 v[0:1], v[56:57], v[48:49], v[0:1] op_sel_hi:[0,1,1]
	v_pk_fma_f32 v[2:3], v[56:57], v[50:51], v[2:3] op_sel_hi:[0,1,1]
	v_add_f32_dpp v4, v4, v4 row_half_mirror row_mask:0xf bank_mask:0xf bound_ctrl:1
	ds_read_b128 v[12:15], v114 offset:6144
	ds_read_b128 v[16:19], v114 offset:6400
	v_add_f32_dpp v4, v4, v4 row_mirror row_mask:0xf bank_mask:0xf bound_ctrl:1
	v_pk_fma_f32 v[0:1], v[4:5], v[44:45], v[0:1] op_sel_hi:[0,1,1] neg_lo:[1,0,0] neg_hi:[1,0,0]
	v_pk_fma_f32 v[2:3], v[4:5], v[46:47], v[2:3] op_sel_hi:[0,1,1] neg_lo:[1,0,0] neg_hi:[1,0,0]
	ds_read_b128 v[20:23], v114 offset:6656
	ds_read_b128 v[24:27], v114 offset:6912
	ds_read_b128 v[28:31], v114 offset:7168
	ds_read_b32 v32, v115 offset:6144
	s_waitcnt lgkmcnt(14)
	v_pk_mul_f32 v[4:5], v[0:1], v[72:73]
	v_pk_mul_f32 v[6:7], v[0:1], v[84:85]
	v_pk_fma_f32 v[4:5], v[2:3], v[74:75], v[4:5]
	v_pk_fma_f32 v[6:7], v[2:3], v[86:87], v[6:7]
	v_add_f32_e32 v4, v4, v5
	v_add_f32_e32 v6, v6, v7
	v_pk_mul_f32 v[0:1], v[0:1], v[68:69]
	v_add_f32_dpp v4, v4, v4 quad_perm:[1,0,3,2] row_mask:0xf bank_mask:0xf bound_ctrl:1
	v_pk_mul_f32 v[2:3], v[2:3], v[70:71]
	ds_write_b32 v10, v6 offset:2048
	v_add_f32_dpp v4, v4, v4 quad_perm:[2,3,0,1] row_mask:0xf bank_mask:0xf bound_ctrl:1
	v_pk_fma_f32 v[0:1], v[88:89], v[80:81], v[0:1] op_sel_hi:[0,1,1]
	v_pk_fma_f32 v[2:3], v[88:89], v[82:83], v[2:3] op_sel_hi:[0,1,1]
	v_add_f32_dpp v4, v4, v4 row_half_mirror row_mask:0xf bank_mask:0xf bound_ctrl:1
	ds_read_b128 v[36:39], v114 offset:7680
	ds_read_b128 v[40:43], v114 offset:7936
	v_add_f32_dpp v4, v4, v4 row_mirror row_mask:0xf bank_mask:0xf bound_ctrl:1
	v_pk_fma_f32 v[0:1], v[4:5], v[76:77], v[0:1] op_sel_hi:[0,1,1] neg_lo:[1,0,0] neg_hi:[1,0,0]
	v_pk_fma_f32 v[2:3], v[4:5], v[78:79], v[2:3] op_sel_hi:[0,1,1] neg_lo:[1,0,0] neg_hi:[1,0,0]
	ds_read_b128 v[44:47], v114 offset:8192
	ds_read_b128 v[48:51], v114 offset:8448
	ds_read_b128 v[52:55], v114 offset:8704
	ds_read_b32 v56, v115 offset:7680
	s_waitcnt lgkmcnt(14)
	v_pk_mul_f32 v[4:5], v[0:1], v[96:97]
	v_pk_mul_f32 v[6:7], v[0:1], v[108:109]
	v_pk_fma_f32 v[4:5], v[2:3], v[98:99], v[4:5]
	v_pk_fma_f32 v[6:7], v[2:3], v[110:111], v[6:7]
	v_add_f32_e32 v4, v4, v5
	v_add_f32_e32 v6, v6, v7
	v_pk_mul_f32 v[0:1], v[0:1], v[92:93]
	v_add_f32_dpp v4, v4, v4 quad_perm:[1,0,3,2] row_mask:0xf bank_mask:0xf bound_ctrl:1
	v_pk_mul_f32 v[2:3], v[2:3], v[94:95]
	ds_write_b32 v10, v6 offset:3072
	v_add_f32_dpp v4, v4, v4 quad_perm:[2,3,0,1] row_mask:0xf bank_mask:0xf bound_ctrl:1
	v_pk_fma_f32 v[0:1], v[112:113], v[104:105], v[0:1] op_sel_hi:[0,1,1]
	v_pk_fma_f32 v[2:3], v[112:113], v[106:107], v[2:3] op_sel_hi:[0,1,1]
	v_add_f32_dpp v4, v4, v4 row_half_mirror row_mask:0xf bank_mask:0xf bound_ctrl:1
	ds_read_b128 v[68:71], v114 offset:9216
	ds_read_b128 v[72:75], v114 offset:9472
	v_add_f32_dpp v4, v4, v4 row_mirror row_mask:0xf bank_mask:0xf bound_ctrl:1
	v_pk_fma_f32 v[0:1], v[4:5], v[100:101], v[0:1] op_sel_hi:[0,1,1] neg_lo:[1,0,0] neg_hi:[1,0,0]
	v_pk_fma_f32 v[2:3], v[4:5], v[102:103], v[2:3] op_sel_hi:[0,1,1] neg_lo:[1,0,0] neg_hi:[1,0,0]
	ds_read_b128 v[76:79], v114 offset:9728
	ds_read_b128 v[80:83], v114 offset:9984
	ds_read_b128 v[84:87], v114 offset:10240
	ds_read_b32 v88, v115 offset:9216
	s_waitcnt lgkmcnt(14)
	v_pk_mul_f32 v[4:5], v[0:1], v[16:17]
	v_pk_mul_f32 v[6:7], v[0:1], v[28:29]
	v_pk_fma_f32 v[4:5], v[2:3], v[18:19], v[4:5]
	v_pk_fma_f32 v[6:7], v[2:3], v[30:31], v[6:7]
	v_add_f32_e32 v4, v4, v5
	v_add_f32_e32 v6, v6, v7
	v_pk_mul_f32 v[0:1], v[0:1], v[12:13]
	v_add_f32_dpp v4, v4, v4 quad_perm:[1,0,3,2] row_mask:0xf bank_mask:0xf bound_ctrl:1
	v_pk_mul_f32 v[2:3], v[2:3], v[14:15]
	ds_write_b32 v10, v6 offset:4096
	v_add_f32_dpp v4, v4, v4 quad_perm:[2,3,0,1] row_mask:0xf bank_mask:0xf bound_ctrl:1
	v_pk_fma_f32 v[0:1], v[32:33], v[24:25], v[0:1] op_sel_hi:[0,1,1]
	v_pk_fma_f32 v[2:3], v[32:33], v[26:27], v[2:3] op_sel_hi:[0,1,1]
	v_add_f32_dpp v4, v4, v4 row_half_mirror row_mask:0xf bank_mask:0xf bound_ctrl:1
	ds_read_b128 v[92:95], v114 offset:10752
	ds_read_b128 v[96:99], v114 offset:11008
	v_add_f32_dpp v4, v4, v4 row_mirror row_mask:0xf bank_mask:0xf bound_ctrl:1
	v_pk_fma_f32 v[0:1], v[4:5], v[20:21], v[0:1] op_sel_hi:[0,1,1] neg_lo:[1,0,0] neg_hi:[1,0,0]
	v_pk_fma_f32 v[2:3], v[4:5], v[22:23], v[2:3] op_sel_hi:[0,1,1] neg_lo:[1,0,0] neg_hi:[1,0,0]
	ds_read_b128 v[100:103], v114 offset:11264
	ds_read_b128 v[104:107], v114 offset:11520
	ds_read_b128 v[108:111], v114 offset:11776
	ds_read_b32 v112, v115 offset:10752
	s_waitcnt lgkmcnt(14)
	v_pk_mul_f32 v[4:5], v[0:1], v[40:41]
	v_pk_mul_f32 v[6:7], v[0:1], v[52:53]
	v_pk_fma_f32 v[4:5], v[2:3], v[42:43], v[4:5]
	v_pk_fma_f32 v[6:7], v[2:3], v[54:55], v[6:7]
	v_add_f32_e32 v4, v4, v5
	v_add_f32_e32 v6, v6, v7
	v_pk_mul_f32 v[0:1], v[0:1], v[36:37]
	v_add_f32_dpp v4, v4, v4 quad_perm:[1,0,3,2] row_mask:0xf bank_mask:0xf bound_ctrl:1
	v_pk_mul_f32 v[2:3], v[2:3], v[38:39]
	ds_write_b32 v10, v6 offset:5120
	v_add_f32_dpp v4, v4, v4 quad_perm:[2,3,0,1] row_mask:0xf bank_mask:0xf bound_ctrl:1
	v_pk_fma_f32 v[0:1], v[56:57], v[48:49], v[0:1] op_sel_hi:[0,1,1]
	v_pk_fma_f32 v[2:3], v[56:57], v[50:51], v[2:3] op_sel_hi:[0,1,1]
	v_add_f32_dpp v4, v4, v4 row_half_mirror row_mask:0xf bank_mask:0xf bound_ctrl:1
	ds_read_b128 v[12:15], v114 offset:12288
	ds_read_b128 v[16:19], v114 offset:12544
	v_add_f32_dpp v4, v4, v4 row_mirror row_mask:0xf bank_mask:0xf bound_ctrl:1
	v_pk_fma_f32 v[0:1], v[4:5], v[44:45], v[0:1] op_sel_hi:[0,1,1] neg_lo:[1,0,0] neg_hi:[1,0,0]
	v_pk_fma_f32 v[2:3], v[4:5], v[46:47], v[2:3] op_sel_hi:[0,1,1] neg_lo:[1,0,0] neg_hi:[1,0,0]
	ds_read_b128 v[20:23], v114 offset:12800
	ds_read_b128 v[24:27], v114 offset:13056
	ds_read_b128 v[28:31], v114 offset:13312
	ds_read_b32 v32, v115 offset:12288
	s_waitcnt lgkmcnt(14)
	v_pk_mul_f32 v[4:5], v[0:1], v[72:73]
	v_pk_mul_f32 v[6:7], v[0:1], v[84:85]
	v_pk_fma_f32 v[4:5], v[2:3], v[74:75], v[4:5]
	v_pk_fma_f32 v[6:7], v[2:3], v[86:87], v[6:7]
	v_add_f32_e32 v4, v4, v5
	v_add_f32_e32 v6, v6, v7
	v_pk_mul_f32 v[0:1], v[0:1], v[68:69]
	v_add_f32_dpp v4, v4, v4 quad_perm:[1,0,3,2] row_mask:0xf bank_mask:0xf bound_ctrl:1
	v_pk_mul_f32 v[2:3], v[2:3], v[70:71]
	ds_write_b32 v10, v6 offset:6144
	v_add_f32_dpp v4, v4, v4 quad_perm:[2,3,0,1] row_mask:0xf bank_mask:0xf bound_ctrl:1
	v_pk_fma_f32 v[0:1], v[88:89], v[80:81], v[0:1] op_sel_hi:[0,1,1]
	v_pk_fma_f32 v[2:3], v[88:89], v[82:83], v[2:3] op_sel_hi:[0,1,1]
	v_add_f32_dpp v4, v4, v4 row_half_mirror row_mask:0xf bank_mask:0xf bound_ctrl:1
	ds_read_b128 v[36:39], v114 offset:13824
	ds_read_b128 v[40:43], v114 offset:14080
	v_add_f32_dpp v4, v4, v4 row_mirror row_mask:0xf bank_mask:0xf bound_ctrl:1
	v_pk_fma_f32 v[0:1], v[4:5], v[76:77], v[0:1] op_sel_hi:[0,1,1] neg_lo:[1,0,0] neg_hi:[1,0,0]
	v_pk_fma_f32 v[2:3], v[4:5], v[78:79], v[2:3] op_sel_hi:[0,1,1] neg_lo:[1,0,0] neg_hi:[1,0,0]
	ds_read_b128 v[44:47], v114 offset:14336
	ds_read_b128 v[48:51], v114 offset:14592
	ds_read_b128 v[52:55], v114 offset:14848
	ds_read_b32 v56, v115 offset:13824
	s_waitcnt lgkmcnt(14)
	v_pk_mul_f32 v[4:5], v[0:1], v[96:97]
	v_pk_mul_f32 v[6:7], v[0:1], v[108:109]
	v_pk_fma_f32 v[4:5], v[2:3], v[98:99], v[4:5]
	v_pk_fma_f32 v[6:7], v[2:3], v[110:111], v[6:7]
	v_add_f32_e32 v4, v4, v5
	v_add_f32_e32 v6, v6, v7
	v_pk_mul_f32 v[0:1], v[0:1], v[92:93]
	v_add_f32_dpp v4, v4, v4 quad_perm:[1,0,3,2] row_mask:0xf bank_mask:0xf bound_ctrl:1
	v_pk_mul_f32 v[2:3], v[2:3], v[94:95]
	ds_write_b32 v10, v6 offset:7168
	v_add_f32_dpp v4, v4, v4 quad_perm:[2,3,0,1] row_mask:0xf bank_mask:0xf bound_ctrl:1
	v_pk_fma_f32 v[0:1], v[112:113], v[104:105], v[0:1] op_sel_hi:[0,1,1]
	v_pk_fma_f32 v[2:3], v[112:113], v[106:107], v[2:3] op_sel_hi:[0,1,1]
	v_add_f32_dpp v4, v4, v4 row_half_mirror row_mask:0xf bank_mask:0xf bound_ctrl:1
	ds_read_b128 v[68:71], v114 offset:15360
	ds_read_b128 v[72:75], v114 offset:15616
	v_add_f32_dpp v4, v4, v4 row_mirror row_mask:0xf bank_mask:0xf bound_ctrl:1
	v_pk_fma_f32 v[0:1], v[4:5], v[100:101], v[0:1] op_sel_hi:[0,1,1] neg_lo:[1,0,0] neg_hi:[1,0,0]
	v_pk_fma_f32 v[2:3], v[4:5], v[102:103], v[2:3] op_sel_hi:[0,1,1] neg_lo:[1,0,0] neg_hi:[1,0,0]
	ds_read_b128 v[76:79], v114 offset:15872
	ds_read_b128 v[80:83], v114 offset:16128
	ds_read_b128 v[84:87], v114 offset:16384
	ds_read_b32 v88, v115 offset:15360
	s_waitcnt lgkmcnt(14)
	v_pk_mul_f32 v[4:5], v[0:1], v[16:17]
	v_pk_mul_f32 v[6:7], v[0:1], v[28:29]
	v_pk_fma_f32 v[4:5], v[2:3], v[18:19], v[4:5]
	v_pk_fma_f32 v[6:7], v[2:3], v[30:31], v[6:7]
	v_add_f32_e32 v4, v4, v5
	v_add_f32_e32 v6, v6, v7
	v_pk_mul_f32 v[0:1], v[0:1], v[12:13]
	v_add_f32_dpp v4, v4, v4 quad_perm:[1,0,3,2] row_mask:0xf bank_mask:0xf bound_ctrl:1
	v_pk_mul_f32 v[2:3], v[2:3], v[14:15]
	ds_write_b32 v10, v6 offset:8192
	v_add_f32_dpp v4, v4, v4 quad_perm:[2,3,0,1] row_mask:0xf bank_mask:0xf bound_ctrl:1
	v_pk_fma_f32 v[0:1], v[32:33], v[24:25], v[0:1] op_sel_hi:[0,1,1]
	v_pk_fma_f32 v[2:3], v[32:33], v[26:27], v[2:3] op_sel_hi:[0,1,1]
	v_add_f32_dpp v4, v4, v4 row_half_mirror row_mask:0xf bank_mask:0xf bound_ctrl:1
	ds_read_b128 v[92:95], v114 offset:16896
	ds_read_b128 v[96:99], v114 offset:17152
	v_add_f32_dpp v4, v4, v4 row_mirror row_mask:0xf bank_mask:0xf bound_ctrl:1
	v_pk_fma_f32 v[0:1], v[4:5], v[20:21], v[0:1] op_sel_hi:[0,1,1] neg_lo:[1,0,0] neg_hi:[1,0,0]
	v_pk_fma_f32 v[2:3], v[4:5], v[22:23], v[2:3] op_sel_hi:[0,1,1] neg_lo:[1,0,0] neg_hi:[1,0,0]
	ds_read_b128 v[100:103], v114 offset:17408
	ds_read_b128 v[104:107], v114 offset:17664
	ds_read_b128 v[108:111], v114 offset:17920
	ds_read_b32 v112, v115 offset:16896
	s_waitcnt lgkmcnt(14)
	v_pk_mul_f32 v[4:5], v[0:1], v[40:41]
	v_pk_mul_f32 v[6:7], v[0:1], v[52:53]
	v_pk_fma_f32 v[4:5], v[2:3], v[42:43], v[4:5]
	v_pk_fma_f32 v[6:7], v[2:3], v[54:55], v[6:7]
	v_add_f32_e32 v4, v4, v5
	v_add_f32_e32 v6, v6, v7
	v_pk_mul_f32 v[0:1], v[0:1], v[36:37]
	v_add_f32_dpp v4, v4, v4 quad_perm:[1,0,3,2] row_mask:0xf bank_mask:0xf bound_ctrl:1
	v_pk_mul_f32 v[2:3], v[2:3], v[38:39]
	ds_write_b32 v10, v6 offset:9216
	v_add_f32_dpp v4, v4, v4 quad_perm:[2,3,0,1] row_mask:0xf bank_mask:0xf bound_ctrl:1
	v_pk_fma_f32 v[0:1], v[56:57], v[48:49], v[0:1] op_sel_hi:[0,1,1]
	v_pk_fma_f32 v[2:3], v[56:57], v[50:51], v[2:3] op_sel_hi:[0,1,1]
	v_add_f32_dpp v4, v4, v4 row_half_mirror row_mask:0xf bank_mask:0xf bound_ctrl:1
	ds_read_b128 v[12:15], v114 offset:18432
	ds_read_b128 v[16:19], v114 offset:18688
	v_add_f32_dpp v4, v4, v4 row_mirror row_mask:0xf bank_mask:0xf bound_ctrl:1
	v_pk_fma_f32 v[0:1], v[4:5], v[44:45], v[0:1] op_sel_hi:[0,1,1] neg_lo:[1,0,0] neg_hi:[1,0,0]
	v_pk_fma_f32 v[2:3], v[4:5], v[46:47], v[2:3] op_sel_hi:[0,1,1] neg_lo:[1,0,0] neg_hi:[1,0,0]
	ds_read_b128 v[20:23], v114 offset:18944
	ds_read_b128 v[24:27], v114 offset:19200
	ds_read_b128 v[28:31], v114 offset:19456
	ds_read_b32 v32, v115 offset:18432
	s_waitcnt lgkmcnt(14)
	v_pk_mul_f32 v[4:5], v[0:1], v[72:73]
	v_pk_mul_f32 v[6:7], v[0:1], v[84:85]
	v_pk_fma_f32 v[4:5], v[2:3], v[74:75], v[4:5]
	v_pk_fma_f32 v[6:7], v[2:3], v[86:87], v[6:7]
	v_add_f32_e32 v4, v4, v5
	v_add_f32_e32 v6, v6, v7
	v_pk_mul_f32 v[0:1], v[0:1], v[68:69]
	v_add_f32_dpp v4, v4, v4 quad_perm:[1,0,3,2] row_mask:0xf bank_mask:0xf bound_ctrl:1
	v_pk_mul_f32 v[2:3], v[2:3], v[70:71]
	ds_write_b32 v10, v6 offset:10240
	v_add_f32_dpp v4, v4, v4 quad_perm:[2,3,0,1] row_mask:0xf bank_mask:0xf bound_ctrl:1
	v_pk_fma_f32 v[0:1], v[88:89], v[80:81], v[0:1] op_sel_hi:[0,1,1]
	v_pk_fma_f32 v[2:3], v[88:89], v[82:83], v[2:3] op_sel_hi:[0,1,1]
	v_add_f32_dpp v4, v4, v4 row_half_mirror row_mask:0xf bank_mask:0xf bound_ctrl:1
	ds_read_b128 v[36:39], v114 offset:19968
	ds_read_b128 v[40:43], v114 offset:20224
	v_add_f32_dpp v4, v4, v4 row_mirror row_mask:0xf bank_mask:0xf bound_ctrl:1
	v_pk_fma_f32 v[0:1], v[4:5], v[76:77], v[0:1] op_sel_hi:[0,1,1] neg_lo:[1,0,0] neg_hi:[1,0,0]
	v_pk_fma_f32 v[2:3], v[4:5], v[78:79], v[2:3] op_sel_hi:[0,1,1] neg_lo:[1,0,0] neg_hi:[1,0,0]
	ds_read_b128 v[44:47], v114 offset:20480
	ds_read_b128 v[48:51], v114 offset:20736
	ds_read_b128 v[52:55], v114 offset:20992
	ds_read_b32 v56, v115 offset:19968
	s_waitcnt lgkmcnt(14)
	v_pk_mul_f32 v[4:5], v[0:1], v[96:97]
	v_pk_mul_f32 v[6:7], v[0:1], v[108:109]
	v_pk_fma_f32 v[4:5], v[2:3], v[98:99], v[4:5]
	v_pk_fma_f32 v[6:7], v[2:3], v[110:111], v[6:7]
	v_add_f32_e32 v4, v4, v5
	v_add_f32_e32 v6, v6, v7
	v_pk_mul_f32 v[0:1], v[0:1], v[92:93]
	v_add_f32_dpp v4, v4, v4 quad_perm:[1,0,3,2] row_mask:0xf bank_mask:0xf bound_ctrl:1
	v_pk_mul_f32 v[2:3], v[2:3], v[94:95]
	ds_write_b32 v10, v6 offset:11264
	v_add_f32_dpp v4, v4, v4 quad_perm:[2,3,0,1] row_mask:0xf bank_mask:0xf bound_ctrl:1
	v_pk_fma_f32 v[0:1], v[112:113], v[104:105], v[0:1] op_sel_hi:[0,1,1]
	v_pk_fma_f32 v[2:3], v[112:113], v[106:107], v[2:3] op_sel_hi:[0,1,1]
	v_add_f32_dpp v4, v4, v4 row_half_mirror row_mask:0xf bank_mask:0xf bound_ctrl:1
	ds_read_b128 v[68:71], v114 offset:21504
	ds_read_b128 v[72:75], v114 offset:21760
	v_add_f32_dpp v4, v4, v4 row_mirror row_mask:0xf bank_mask:0xf bound_ctrl:1
	v_pk_fma_f32 v[0:1], v[4:5], v[100:101], v[0:1] op_sel_hi:[0,1,1] neg_lo:[1,0,0] neg_hi:[1,0,0]
	v_pk_fma_f32 v[2:3], v[4:5], v[102:103], v[2:3] op_sel_hi:[0,1,1] neg_lo:[1,0,0] neg_hi:[1,0,0]
	ds_read_b128 v[76:79], v114 offset:22016
	ds_read_b128 v[80:83], v114 offset:22272
	ds_read_b128 v[84:87], v114 offset:22528
	ds_read_b32 v88, v115 offset:21504
	s_waitcnt lgkmcnt(14)
	v_pk_mul_f32 v[4:5], v[0:1], v[16:17]
	v_pk_mul_f32 v[6:7], v[0:1], v[28:29]
	v_pk_fma_f32 v[4:5], v[2:3], v[18:19], v[4:5]
	v_pk_fma_f32 v[6:7], v[2:3], v[30:31], v[6:7]
	v_add_f32_e32 v4, v4, v5
	v_add_f32_e32 v6, v6, v7
	v_pk_mul_f32 v[0:1], v[0:1], v[12:13]
	v_add_f32_dpp v4, v4, v4 quad_perm:[1,0,3,2] row_mask:0xf bank_mask:0xf bound_ctrl:1
	v_pk_mul_f32 v[2:3], v[2:3], v[14:15]
	ds_write_b32 v10, v6 offset:12288
	v_add_f32_dpp v4, v4, v4 quad_perm:[2,3,0,1] row_mask:0xf bank_mask:0xf bound_ctrl:1
	v_pk_fma_f32 v[0:1], v[32:33], v[24:25], v[0:1] op_sel_hi:[0,1,1]
	v_pk_fma_f32 v[2:3], v[32:33], v[26:27], v[2:3] op_sel_hi:[0,1,1]
	v_add_f32_dpp v4, v4, v4 row_half_mirror row_mask:0xf bank_mask:0xf bound_ctrl:1
	ds_read_b128 v[92:95], v114 offset:23040
	ds_read_b128 v[96:99], v114 offset:23296
	v_add_f32_dpp v4, v4, v4 row_mirror row_mask:0xf bank_mask:0xf bound_ctrl:1
	v_pk_fma_f32 v[0:1], v[4:5], v[20:21], v[0:1] op_sel_hi:[0,1,1] neg_lo:[1,0,0] neg_hi:[1,0,0]
	v_pk_fma_f32 v[2:3], v[4:5], v[22:23], v[2:3] op_sel_hi:[0,1,1] neg_lo:[1,0,0] neg_hi:[1,0,0]
	ds_read_b128 v[100:103], v114 offset:23552
	ds_read_b128 v[104:107], v114 offset:23808
	ds_read_b128 v[108:111], v114 offset:24064
	ds_read_b32 v112, v115 offset:23040
	s_waitcnt lgkmcnt(14)
	v_pk_mul_f32 v[4:5], v[0:1], v[40:41]
	v_pk_mul_f32 v[6:7], v[0:1], v[52:53]
	v_pk_fma_f32 v[4:5], v[2:3], v[42:43], v[4:5]
	v_pk_fma_f32 v[6:7], v[2:3], v[54:55], v[6:7]
	v_add_f32_e32 v4, v4, v5
	v_add_f32_e32 v6, v6, v7
	v_pk_mul_f32 v[0:1], v[0:1], v[36:37]
	v_add_f32_dpp v4, v4, v4 quad_perm:[1,0,3,2] row_mask:0xf bank_mask:0xf bound_ctrl:1
	v_pk_mul_f32 v[2:3], v[2:3], v[38:39]
	ds_write_b32 v10, v6 offset:13312
	v_add_f32_dpp v4, v4, v4 quad_perm:[2,3,0,1] row_mask:0xf bank_mask:0xf bound_ctrl:1
	v_pk_fma_f32 v[0:1], v[56:57], v[48:49], v[0:1] op_sel_hi:[0,1,1]
	v_pk_fma_f32 v[2:3], v[56:57], v[50:51], v[2:3] op_sel_hi:[0,1,1]
	v_add_f32_dpp v4, v4, v4 row_half_mirror row_mask:0xf bank_mask:0xf bound_ctrl:1
	ds_read_b128 v[12:15], v116 offset:0
	ds_read_b128 v[16:19], v116 offset:256
	v_add_f32_dpp v4, v4, v4 row_mirror row_mask:0xf bank_mask:0xf bound_ctrl:1
	v_pk_fma_f32 v[0:1], v[4:5], v[44:45], v[0:1] op_sel_hi:[0,1,1] neg_lo:[1,0,0] neg_hi:[1,0,0]
	v_pk_fma_f32 v[2:3], v[4:5], v[46:47], v[2:3] op_sel_hi:[0,1,1] neg_lo:[1,0,0] neg_hi:[1,0,0]
	ds_read_b128 v[20:23], v116 offset:512
	ds_read_b128 v[24:27], v116 offset:768
	ds_read_b128 v[28:31], v116 offset:1024
	ds_read_b32 v32, v117 offset:0
	s_waitcnt lgkmcnt(14)
	v_pk_mul_f32 v[4:5], v[0:1], v[72:73]
	v_pk_mul_f32 v[6:7], v[0:1], v[84:85]
	v_pk_fma_f32 v[4:5], v[2:3], v[74:75], v[4:5]
	v_pk_fma_f32 v[6:7], v[2:3], v[86:87], v[6:7]
	v_add_f32_e32 v4, v4, v5
	v_add_f32_e32 v6, v6, v7
	v_pk_mul_f32 v[0:1], v[0:1], v[68:69]
	v_add_f32_dpp v4, v4, v4 quad_perm:[1,0,3,2] row_mask:0xf bank_mask:0xf bound_ctrl:1
	v_pk_mul_f32 v[2:3], v[2:3], v[70:71]
	ds_write_b32 v10, v6 offset:14336
	v_add_f32_dpp v4, v4, v4 quad_perm:[2,3,0,1] row_mask:0xf bank_mask:0xf bound_ctrl:1
	v_pk_fma_f32 v[0:1], v[88:89], v[80:81], v[0:1] op_sel_hi:[0,1,1]
	v_pk_fma_f32 v[2:3], v[88:89], v[82:83], v[2:3] op_sel_hi:[0,1,1]
	v_add_f32_dpp v4, v4, v4 row_half_mirror row_mask:0xf bank_mask:0xf bound_ctrl:1
	ds_read_b128 v[36:39], v116 offset:1536
	ds_read_b128 v[40:43], v116 offset:1792
	v_add_f32_dpp v4, v4, v4 row_mirror row_mask:0xf bank_mask:0xf bound_ctrl:1
	v_pk_fma_f32 v[0:1], v[4:5], v[76:77], v[0:1] op_sel_hi:[0,1,1] neg_lo:[1,0,0] neg_hi:[1,0,0]
	v_pk_fma_f32 v[2:3], v[4:5], v[78:79], v[2:3] op_sel_hi:[0,1,1] neg_lo:[1,0,0] neg_hi:[1,0,0]
	ds_read_b128 v[44:47], v116 offset:2048
	ds_read_b128 v[48:51], v116 offset:2304
	ds_read_b128 v[52:55], v116 offset:2560
	ds_read_b32 v56, v117 offset:1536
	s_waitcnt lgkmcnt(14)
	v_pk_mul_f32 v[4:5], v[0:1], v[96:97]
	v_pk_mul_f32 v[6:7], v[0:1], v[108:109]
	v_pk_fma_f32 v[4:5], v[2:3], v[98:99], v[4:5]
	v_pk_fma_f32 v[6:7], v[2:3], v[110:111], v[6:7]
	v_add_f32_e32 v4, v4, v5
	v_add_f32_e32 v6, v6, v7
	v_pk_mul_f32 v[0:1], v[0:1], v[92:93]
	v_add_f32_dpp v4, v4, v4 quad_perm:[1,0,3,2] row_mask:0xf bank_mask:0xf bound_ctrl:1
	v_pk_mul_f32 v[2:3], v[2:3], v[94:95]
	ds_write_b32 v10, v6 offset:15360
	v_add_f32_dpp v4, v4, v4 quad_perm:[2,3,0,1] row_mask:0xf bank_mask:0xf bound_ctrl:1
	v_pk_fma_f32 v[0:1], v[112:113], v[104:105], v[0:1] op_sel_hi:[0,1,1]
	v_pk_fma_f32 v[2:3], v[112:113], v[106:107], v[2:3] op_sel_hi:[0,1,1]
	v_add_f32_dpp v4, v4, v4 row_half_mirror row_mask:0xf bank_mask:0xf bound_ctrl:1
	ds_read_b128 v[68:71], v116 offset:3072
	ds_read_b128 v[72:75], v116 offset:3328
	v_add_f32_dpp v4, v4, v4 row_mirror row_mask:0xf bank_mask:0xf bound_ctrl:1
	v_pk_fma_f32 v[0:1], v[4:5], v[100:101], v[0:1] op_sel_hi:[0,1,1] neg_lo:[1,0,0] neg_hi:[1,0,0]
	v_pk_fma_f32 v[2:3], v[4:5], v[102:103], v[2:3] op_sel_hi:[0,1,1] neg_lo:[1,0,0] neg_hi:[1,0,0]
	ds_read_b128 v[76:79], v116 offset:3584
	ds_read_b128 v[80:83], v116 offset:3840
	ds_read_b128 v[84:87], v116 offset:4096
	ds_read_b32 v88, v117 offset:3072
	s_waitcnt lgkmcnt(6)
	s_barrier
	s_mov_b32 s0, s1
	s_add_i32 s1, s1, 0x6000
	s_cmp_eq_u32 s1, 0x12000
	s_cselect_b32 s1, 0, s1
	v_mov_b32_e32 v114, v116
	v_mov_b32_e32 v115, v117
	v_add_u32_e32 v116, s1, v8
	v_add_u32_e32 v117, s1, v9
	v_add_u32_e32 v10, s24, v10
	s_sub_i32 s24, 0, s24
	s_sub_u32 s34, s34, 1
	s_cmp_lg_u32 s34, 0
	s_cbranch_scc1 .Lb2_scan_loop
	s_setprio 0
	s_waitcnt lgkmcnt(0)
	global_store_dwordx4 v11, v[0:3], s[40:41]
	s_branch .Lb2_u_next
.Lb2_loader:
	v_add_u32_e32 v61, 0xffffff00, v133
	v_lshrrev_b32_e32 v62, 5, v61
	v_mul_u32_u24_e32 v48, 0x600, v62
	v_and_b32_e32 v63, 31, v61
	v_lshl_add_u32 v48, v63, 4, v48
	v_add_u32_e32 v49, 0x3000, v48
	v_lshlrev_b32_e32 v51, 6, v61
	v_add_u32_e32 v51, 0x16000, v51
	v_lshrrev_b32_e32 v62, 4, v61
	v_lshlrev_b32_e32 v60, 11, v62
	v_and_b32_e32 v63, 15, v61
	v_lshl_add_u32 v60, v63, 2, v60
	s_lshr_b32 s21, s20, 3
	s_lshl_b32 s21, s21, 22
	s_and_b32 s23, s20, 7
	s_lshl_b32 s23, s23, 8
	s_add_i32 s21, s21, s23
	s_lshl_b32 s23, s33, 6
	s_add_i32 s21, s21, s23
	s_add_u32 s21, s21, 0x19314000
	s_add_u32 s36, s94, s21
	s_addc_u32 s37, s95, 0
	s_movk_i32 s34, 0x40
	s_mov_b32 s35, 0
	s_mov_b32 s2, 0xc000
	s_mov_b32 s24, 0x4000
	global_load_dwordx4 v[0:3], v48, s[28:29]
	global_load_dwordx4 v[4:7], v48, s[28:29] offset:512
	global_load_dwordx4 v[8:11], v48, s[28:29] offset:1024
	global_load_dwordx4 v[12:15], v49, s[28:29]
	global_load_dwordx4 v[16:19], v49, s[28:29] offset:512
	global_load_dwordx4 v[20:23], v49, s[28:29] offset:1024
	s_add_u32 s28, s28, 0x6000
	s_addc_u32 s29, s29, 0
	global_load_dwordx4 v[24:27], v48, s[28:29]
	global_load_dwordx4 v[28:31], v48, s[28:29] offset:512
	global_load_dwordx4 v[32:35], v48, s[28:29] offset:1024
	global_load_dwordx4 v[36:39], v49, s[28:29]
	global_load_dwordx4 v[40:43], v49, s[28:29] offset:512
	global_load_dwordx4 v[44:47], v49, s[28:29] offset:1024
	s_add_u32 s28, s28, 0x6000
	s_addc_u32 s29, s29, 0
	s_waitcnt vmcnt(0)
	v_mov_b32_e32 v50, v48
	ds_write_b128 v50, v[0:3] offset:0
	ds_write_b128 v50, v[4:7] offset:512
	ds_write_b128 v50, v[8:11] offset:1024
	ds_write_b128 v50, v[12:15] offset:12288
	ds_write_b128 v50, v[16:19] offset:12800
	ds_write_b128 v50, v[20:23] offset:13312
	v_add_u32_e32 v50, 0x6000, v48
	ds_write_b128 v50, v[24:27] offset:0
	ds_write_b128 v50, v[28:31] offset:512
	ds_write_b128 v50, v[32:35] offset:1024
	ds_write_b128 v50, v[36:39] offset:12288
	ds_write_b128 v50, v[40:43] offset:12800
	ds_write_b128 v50, v[44:47] offset:13312
	global_load_dwordx4 v[0:3], v48, s[28:29]
	global_load_dwordx4 v[4:7], v48, s[28:29] offset:512
	global_load_dwordx4 v[8:11], v48, s[28:29] offset:1024
	global_load_dwordx4 v[12:15], v49, s[28:29]
	global_load_dwordx4 v[16:19], v49, s[28:29] offset:512
	global_load_dwordx4 v[20:23], v49, s[28:29] offset:1024
	s_add_u32 s28, s28, 0x6000
	s_addc_u32 s29, s29, 0
	global_load_dwordx4 v[24:27], v48, s[28:29]
	global_load_dwordx4 v[28:31], v48, s[28:29] offset:512
	global_load_dwordx4 v[32:35], v48, s[28:29] offset:1024
	global_load_dwordx4 v[36:39], v49, s[28:29]
	global_load_dwordx4 v[40:43], v49, s[28:29] offset:512
	global_load_dwordx4 v[44:47], v49, s[28:29] offset:1024
	s_add_u32 s28, s28, 0x6000
	s_addc_u32 s29, s29, 0
	s_waitcnt lgkmcnt(0)
	s_barrier
.Lb2_load_loop:
	s_cmp_eq_u32 s35, 0
	s_cbranch_scc1 .Lb2_ld_first
	v_subrev_u32_e32 v51, s24, v51
	s_sub_i32 s24, 0, s24
	ds_read_b128 v[68:71], v51 offset:0
	ds_read_b128 v[72:75], v51 offset:16
	ds_read_b128 v[76:79], v51 offset:32
	ds_read_b128 v[80:83], v51 offset:48
	s_waitcnt lgkmcnt(0)
	v_add_f32_e32 v68, v68, v69
	v_add_f32_e32 v70, v70, v71
	v_add_f32_e32 v72, v72, v73
	v_add_f32_e32 v74, v74, v75
	v_add_f32_e32 v76, v76, v77
	v_add_f32_e32 v78, v78, v79
	v_add_f32_e32 v80, v80, v81
	v_add_f32_e32 v82, v82, v83
	v_add_f32_e32 v68, v68, v70
	v_add_f32_e32 v72, v72, v74
	v_add_f32_e32 v76, v76, v78
	v_add_f32_e32 v80, v80, v82
	v_add_f32_e32 v68, v68, v72
	v_add_f32_e32 v76, v76, v80
	v_add_f32_e32 v68, v68, v76
	global_store_dword v60, v68, s[36:37]
	s_add_u32 s36, s36, 0x8000
	s_addc_u32 s37, s37, 0
.Lb2_ld_first:
	s_mov_b32 s35, 1
	s_waitcnt vmcnt(6)
	v_add_u32_e32 v50, s2, v48
	ds_write_b128 v50, v[0:3] offset:0
	ds_write_b128 v50, v[4:7] offset:512
	ds_write_b128 v50, v[8:11] offset:1024
	ds_write_b128 v50, v[12:15] offset:12288
	ds_write_b128 v50, v[16:19] offset:12800
	ds_write_b128 v50, v[20:23] offset:13312
	s_add_i32 s2, s2, 0x6000
	s_cmp_eq_u32 s2, 0x12000
	s_cselect_b32 s2, 0, s2
	global_load_dwordx4 v[0:3], v48, s[28:29]
	global_load_dwordx4 v[4:7], v48, s[28:29] offset:512
	global_load_dwordx4 v[8:11], v48, s[28:29] offset:1024
	global_load_dwordx4 v[12:15], v49, s[28:29]
	global_load_dwordx4 v[16:19], v49, s[28:29] offset:512
	global_load_dwordx4 v[20:23], v49, s[28:29] offset:1024
	s_add_u32 s28, s28, 0x6000
	s_addc_u32 s29, s29, 0
	s_waitcnt lgkmcnt(0)
	s_barrier
	v_subrev_u32_e32 v51, s24, v51
	s_sub_i32 s24, 0, s24
	ds_read_b128 v[68:71], v51 offset:0
	ds_read_b128 v[72:75], v51 offset:16
	ds_read_b128 v[76:79], v51 offset:32
	ds_read_b128 v[80:83], v51 offset:48
	s_waitcnt lgkmcnt(0)
	v_add_f32_e32 v68, v68, v69
	v_add_f32_e32 v70, v70, v71
	v_add_f32_e32 v72, v72, v73
	v_add_f32_e32 v74, v74, v75
	v_add_f32_e32 v76, v76, v77
	v_add_f32_e32 v78, v78, v79
	v_add_f32_e32 v80, v80, v81
	v_add_f32_e32 v82, v82, v83
	v_add_f32_e32 v68, v68, v70
	v_add_f32_e32 v72, v72, v74
	v_add_f32_e32 v76, v76, v78
	v_add_f32_e32 v80, v80, v82
	v_add_f32_e32 v68, v68, v72
	v_add_f32_e32 v76, v76, v80
	v_add_f32_e32 v68, v68, v76
	global_store_dword v60, v68, s[36:37]
	s_add_u32 s36, s36, 0x8000
	s_addc_u32 s37, s37, 0
	s_waitcnt vmcnt(6)
	v_add_u32_e32 v50, s2, v48
	ds_write_b128 v50, v[24:27] offset:0
	ds_write_b128 v50, v[28:31] offset:512
	ds_write_b128 v50, v[32:35] offset:1024
	ds_write_b128 v50, v[36:39] offset:12288
	ds_write_b128 v50, v[40:43] offset:12800
	ds_write_b128 v50, v[44:47] offset:13312
	s_add_i32 s2, s2, 0x6000
	s_cmp_eq_u32 s2, 0x12000
	s_cselect_b32 s2, 0, s2
	global_load_dwordx4 v[24:27], v48, s[28:29]
	global_load_dwordx4 v[28:31], v48, s[28:29] offset:512
	global_load_dwordx4 v[32:35], v48, s[28:29] offset:1024
	global_load_dwordx4 v[36:39], v49, s[28:29]
	global_load_dwordx4 v[40:43], v49, s[28:29] offset:512
	global_load_dwordx4 v[44:47], v49, s[28:29] offset:1024
	s_add_u32 s28, s28, 0x6000
	s_addc_u32 s29, s29, 0
	s_waitcnt lgkmcnt(0)
	s_barrier
	s_sub_u32 s34, s34, 1
	s_cmp_lg_u32 s34, 0
	s_cbranch_scc1 .Lb2_load_loop
	v_subrev_u32_e32 v51, s24, v51
	s_sub_i32 s24, 0, s24
	ds_read_b128 v[68:71], v51 offset:0
	ds_read_b128 v[72:75], v51 offset:16
	ds_read_b128 v[76:79], v51 offset:32
	ds_read_b128 v[80:83], v51 offset:48
	s_waitcnt lgkmcnt(0)
	v_add_f32_e32 v68, v68, v69
	v_add_f32_e32 v70, v70, v71
	v_add_f32_e32 v72, v72, v73
	v_add_f32_e32 v74, v74, v75
	v_add_f32_e32 v76, v76, v77
	v_add_f32_e32 v78, v78, v79
	v_add_f32_e32 v80, v80, v81
	v_add_f32_e32 v82, v82, v83
	v_add_f32_e32 v68, v68, v70
	v_add_f32_e32 v72, v72, v74
	v_add_f32_e32 v76, v76, v78
	v_add_f32_e32 v80, v80, v82
	v_add_f32_e32 v68, v68, v72
	v_add_f32_e32 v76, v76, v80
	v_add_f32_e32 v68, v68, v76
	global_store_dword v60, v68, s[36:37]
	s_add_u32 s36, s36, 0x8000
	s_addc_u32 s37, s37, 0
